# RWKV: nt hint on the read-once projection/lora row loads (on v52)
# baseline (speedup 1.0000x reference)
; __device__ __forceinline__ float bf2f(bf16_t v) { return __uint_as_float(((unsigned)v) << 16); }
; __device__ __forceinline__ int lane_id_() { int l; asm volatile("v_mbcnt_lo_u32_b32 %0, -1, 0\n\tv_mbcnt_hi_u32_b32 %0, -1, %0" : "=v"(l)); return l; }
; __device__ __forceinline__ void rwkv_phaseA(const Ctx& F, LAS unsigned char* W, unsigned char* X, int b, int h, int c) {
;     const bf16_t* proj = (const bf16_t*)(F.ws + WS_BIG); const bf16_t* LO = (const bf16_t*)(F.ws + WS_LORA);
;     const int lane = lane_id_(), i = lane & 15, g = lane >> 4, col = h * 64 + lane;
;     const float mu_r = F_mu[col], mu_k = F_mu[512 + col], mu_v = F_mu[1024 + col], w0 = F_w0[col], a0 = F_a0[col], k_k = F_k_k[col], k_a = F_k_a[col], r_k = F_r_k[col];
;     float Bc = 0.f, cprev = 1.f;
;     {
;         const unsigned ul0 = (unsigned)lane;
;         const size_t row0 = (size_t)b * S + c * 32;
;         const bf16_t* pb = proj + row0 * IN_EVEN_P + RW_OFF + h * 64; const bf16_t* lb = LO + row0 * 1536 + h * 64;
;         float pr_ = 0.f, pk_ = 0.f, pv_ = 0.f;
;         if (c > 0) { const bf16_t* pp = pb - IN_EVEN_P; pr_ = bf2f(pp[ul0]); pk_ = bf2f(pp[512 + ul0]); pv_ = bf2f(pp[1024 + ul0]); }
.LBB0_792:
	s_andn2_b64 vcc, exec, s[16:17]
	s_waitcnt vmcnt(0) lgkmcnt(0)
	s_barrier
	s_cbranch_vccnz .LBB0_833
	v_mbcnt_lo_u32_b32 v2, -1, 0
	v_mbcnt_hi_u32_b32 v2, -1, v2
	s_load_dwordx2 s[8:9], s[12:13], 0x68
	v_add_u32_e32 v12, s14, v2
	v_ashrrev_i32_e32 v13, 31, v12
	v_lshlrev_b64 v[12:13], 2, v[12:13]
	v_lshl_add_u64 v[14:15], s[36:37], 0, v[12:13]
	v_add_co_u32_e32 v16, vcc, 0x1000, v14
	s_nop 1
	v_addc_co_u32_e32 v17, vcc, 0, v15, vcc
	flat_load_dword v20, v[14:15]
	flat_load_dword v21, v[14:15] offset:2048
	flat_load_dword v22, v[16:17]
	s_load_dwordx2 s[10:11], s[12:13], 0x78
	s_load_dwordx4 s[4:7], s[12:13], 0x90
	s_load_dwordx2 s[60:61], s[12:13], 0xa0
	s_waitcnt lgkmcnt(0)
	v_lshl_add_u64 v[14:15], s[8:9], 0, v[12:13]
	flat_load_dword v23, v[14:15]
	v_lshl_add_u64 v[14:15], s[10:11], 0, v[12:13]
	flat_load_dword v24, v[14:15]
	v_lshl_add_u64 v[14:15], s[4:5], 0, v[12:13]
	flat_load_dword v25, v[14:15]
	v_lshl_add_u64 v[14:15], s[6:7], 0, v[12:13]
	v_lshl_add_u64 v[12:13], s[60:61], 0, v[12:13]
	flat_load_dword v26, v[14:15]
	flat_load_dword v27, v[12:13]
	s_lshl_b32 s4, s22, 2
	s_or_b32 s8, s4, s50
	s_lshl_b32 s4, s8, 5
	s_add_u32 s6, s38, s4
	s_addc_u32 s7, s39, 0
	s_mul_i32 s4, s7, 0x1400
	s_mul_hi_u32 s5, s6, 0x1400
	s_add_i32 s5, s5, s4
	s_mul_i32 s4, s6, 0x1400
	s_add_u32 s4, s46, s4
	s_addc_u32 s5, s47, s5
	s_lshl_b32 s9, s14, 1
	s_add_u32 s4, s4, s9
	s_addc_u32 s5, s5, 0
	s_add_u32 s4, s4, 0xc200540
	s_addc_u32 s5, s5, 0
	s_cmp_eq_u32 s8, 0
	s_cbranch_scc1 .LBB0_795
	s_add_u32 s8, s4, 0xffffec00
	s_addc_u32 s9, s5, -1
	v_mov_b32_e32 v3, v1
	v_add_u32_e32 v0, 0x200, v2
	v_lshl_add_u64 v[12:13], v[2:3], 1, s[8:9]
	v_lshl_add_u64 v[14:15], v[0:1], 1, s[8:9]
	v_add_u32_e32 v0, 0x400, v2
	v_lshl_add_u64 v[16:17], v[0:1], 1, s[8:9]
	global_load_ushort v0, v[14:15], off nt
	global_load_ushort v3, v[16:17], off nt
	s_nop 0
	global_load_ushort v12, v[12:13], off nt
	s_waitcnt vmcnt(0)
	v_lshlrev_b32_e32 v13, 16, v0
	v_lshlrev_b32_e32 v3, 16, v3
	v_lshlrev_b32_e32 v12, 16, v12
	s_branch .LBB0_796

; #define RW_LD8(dst, t8_) do { const unsigned ul = launder_(ul0); _Pragma("unroll") for (int tt = 0; tt < 8; ++tt) { const bf16_t* p = pb + (size_t)(8 * (t8_) + tt) * IN_EVEN_P; const bf16_t* lo = lb + (size_t)(8 * (t8_) + tt) * 1536; \
;             dst[tt][0] = p[ul]; dst[tt][1] = p[512 + ul]; dst[tt][2] = p[1024 + ul]; dst[tt][3] = lo[ul]; dst[tt][4] = lo[512 + ul]; } } while (0)
; __device__ __forceinline__ void rwkv_phaseA(const Ctx& F, LAS unsigned char* W, unsigned char* X, int b, int h, int c) {
;     ...
;         RW_LD8(cur, 0);
.LBB0_796:
	s_mulk_i32 s7, 0xc00
	s_mul_hi_u32 s8, s6, 0xc00
	s_add_i32 s8, s8, s7
	s_mulk_i32 s6, 0xc00
	s_add_u32 s6, s15, s6
	s_addc_u32 s7, s70, s8
	v_mov_b32_e32 v0, v2
	v_mov_b32_e32 v17, v1
	v_add_u32_e32 v16, 0x200, v0
	v_add_u32_e32 v18, 0x400, v0
	v_mov_b32_e32 v19, v1
	s_add_u32 s8, s4, 0x1400
	v_lshlrev_b64 v[14:15], 1, v[0:1]
	v_lshlrev_b64 v[16:17], 1, v[16:17]
	v_lshlrev_b64 v[18:19], 1, v[18:19]
	s_addc_u32 s9, s5, 0
	v_lshl_add_u64 v[38:39], s[8:9], 0, v[14:15]
	v_lshl_add_u64 v[40:41], s[8:9], 0, v[16:17]
	v_lshl_add_u64 v[42:43], s[8:9], 0, v[18:19]
	s_add_u32 s8, s4, 0x2800
	s_addc_u32 s9, s5, 0
	s_add_u32 s10, s6, 0x1800
	v_lshl_add_u64 v[28:29], s[4:5], 0, v[14:15]
	v_lshl_add_u64 v[30:31], s[4:5], 0, v[16:17]
	v_lshl_add_u64 v[34:35], s[6:7], 0, v[14:15]
	v_lshl_add_u64 v[36:37], s[6:7], 0, v[16:17]
	s_addc_u32 s11, s7, 0
	v_lshl_add_u64 v[32:33], s[4:5], 0, v[18:19]
	global_load_ushort v0, v[28:29], off nt
	s_nop 0
	global_load_ushort v29, v[30:31], off nt
	global_load_ushort v28, v[32:33], off nt
	s_nop 0
	global_load_ushort v30, v[34:35], off nt
	global_load_ushort v31, v[36:37], off nt
	global_load_ushort v129, v[38:39], off nt
	global_load_ushort v130, v[36:37], off offset:3072 nt
	global_load_ushort v131, v[34:35], off offset:3072 nt
	v_lshl_add_u64 v[34:35], s[8:9], 0, v[14:15]
	v_lshl_add_u64 v[36:37], s[8:9], 0, v[16:17]
	v_lshl_add_u64 v[38:39], s[8:9], 0, v[18:19]
	s_add_u32 s8, s4, 0x3c00
	s_addc_u32 s9, s5, 0
	v_lshl_add_u64 v[44:45], s[10:11], 0, v[14:15]
	v_lshl_add_u64 v[46:47], s[10:11], 0, v[16:17]
	s_add_u32 s10, s6, 0x2400
	s_addc_u32 s11, s7, 0
	v_lshl_add_u64 v[48:49], s[8:9], 0, v[14:15]
	global_load_ushort v132, v[40:41], off nt
	global_load_ushort v32, v[42:43], off nt
	global_load_ushort v126, v[34:35], off nt
	global_load_ushort v128, v[36:37], off nt
	global_load_ushort v33, v[38:39], off nt
	global_load_ushort v127, v[44:45], off nt
	global_load_ushort v123, v[46:47], off nt
	global_load_ushort v119, v[48:49], off nt
	v_lshl_add_u64 v[34:35], s[8:9], 0, v[16:17]
	v_lshl_add_u64 v[36:37], s[8:9], 0, v[18:19]
	s_add_u32 s8, s4, 0x5000
	s_addc_u32 s9, s5, 0
	v_lshl_add_u64 v[38:39], s[10:11], 0, v[14:15]
	v_lshl_add_u64 v[40:41], s[10:11], 0, v[16:17]
	s_add_u32 s10, s6, 0x3000
	s_addc_u32 s11, s7, 0
	v_lshl_add_u64 v[42:43], s[8:9], 0, v[14:15]
	v_lshl_add_u64 v[44:45], s[8:9], 0, v[16:17]
	v_lshl_add_u64 v[46:47], s[8:9], 0, v[18:19]
	s_add_u32 s8, s4, 0x6400
	s_addc_u32 s9, s5, 0
	v_lshl_add_u64 v[48:49], s[10:11], 0, v[14:15]
	global_load_ushort v122, v[34:35], off nt
	s_nop 0
	global_load_ushort v34, v[36:37], off nt
	global_load_ushort v121, v[38:39], off nt
	global_load_ushort v120, v[40:41], off nt
	global_load_ushort v107, v[42:43], off nt
	global_load_ushort v108, v[44:45], off nt
	global_load_ushort v35, v[46:47], off nt
	global_load_ushort v109, v[48:49], off nt
	v_lshl_add_u64 v[36:37], s[10:11], 0, v[16:17]
	s_add_u32 s10, s6, 0x3c00
	s_addc_u32 s11, s7, 0
	v_lshl_add_u64 v[38:39], s[8:9], 0, v[14:15]
	v_lshl_add_u64 v[40:41], s[8:9], 0, v[16:17]
	v_lshl_add_u64 v[42:43], s[8:9], 0, v[18:19]
	s_add_u32 s8, s4, 0x7800
	s_addc_u32 s9, s5, 0
	v_lshl_add_u64 v[44:45], s[10:11], 0, v[14:15]
	v_lshl_add_u64 v[46:47], s[10:11], 0, v[16:17]
	s_add_u32 s10, s6, 0x4800
	s_addc_u32 s11, s7, 0
	v_lshl_add_u64 v[48:49], s[8:9], 0, v[14:15]
	v_lshl_add_u64 v[52:53], s[8:9], 0, v[16:17]
	global_load_ushort v118, v[36:37], off nt
	global_load_ushort v103, v[38:39], off nt
	global_load_ushort v105, v[40:41], off nt
	s_nop 0
	global_load_ushort v39, v[42:43], off nt
	global_load_ushort v104, v[44:45], off nt
	global_load_ushort v95, v[46:47], off nt
	global_load_ushort v50, v[48:49], off nt
	global_load_ushort v51, v[52:53], off nt
	v_lshl_add_u64 v[36:37], s[8:9], 0, v[18:19]
	s_add_u32 s8, s4, 0x8c00
	s_addc_u32 s9, s5, 0
	v_lshl_add_u64 v[42:43], s[10:11], 0, v[14:15]
	v_lshl_add_u64 v[44:45], s[10:11], 0, v[16:17]
	s_add_u32 s10, s6, 0x5400
	s_addc_u32 s11, s7, 0
	v_lshl_add_u64 v[40:41], s[8:9], 0, v[14:15]
	v_lshl_add_u64 v[46:47], s[8:9], 0, v[16:17]
	global_load_ushort v38, v[40:41], off nt
	s_nop 0
	global_load_ushort v46, v[46:47], off nt
	v_lshl_add_u64 v[18:19], s[8:9], 0, v[18:19]
	v_lshl_add_u64 v[14:15], s[10:11], 0, v[14:15]
	v_lshl_add_u64 v[16:17], s[10:11], 0, v[16:17]
	global_load_ushort v40, v[36:37], off nt
	global_load_ushort v94, v[42:43], off nt
	global_load_ushort v67, v[44:45], off nt
	global_load_ushort v41, v[18:19], off nt
	global_load_ushort v48, v[14:15], off nt
	s_nop 0
	global_load_ushort v44, v[16:17], off nt
	v_mul_lo_u32 v14, v2, s96
	v_lshl_add_u32 v36, v2, 1, s43
	v_cmp_eq_u32_e32 vcc, 0, v2
	v_add_u32_e32 v37, s93, v14
	v_mov_b32_e32 v133, 1.0
	s_mov_b64 s[8:9], 0
	s_mov_b64 s[10:11], 0x30204800
	s_mov_b32 s23, 8
	s_waitcnt vmcnt(0)
	v_perm_b32 v43, v46, v38, s97
	v_mov_b32_e32 v38, 0
; __device__ __forceinline__ unsigned launder_(unsigned x) { asm volatile("" : "+v"(x)); return x; }
; #define RW_LD8(dst, t8_) do { const unsigned ul = launder_(ul0); _Pragma("unroll") for (int tt = 0; tt < 8; ++tt) { const bf16_t* p = pb + (size_t)(8 * (t8_) + tt) * IN_EVEN_P; const bf16_t* lo = lb + (size_t)(8 * (t8_) + tt) * 1536; \
;             dst[tt][0] = p[ul]; dst[tt][1] = p[512 + ul]; dst[tt][2] = p[1024 + ul]; dst[tt][3] = lo[ul]; dst[tt][4] = lo[512 + ul]; } } while (0)
; __device__ __forceinline__ void rwkv_phaseA(const Ctx& F, LAS unsigned char* W, unsigned char* X, int b, int h, int c) {
;     ...
;         RW_LD8(cur, 0);
; #pragma unroll 1
;         for (int t8 = 0; t8 < 4; ++t8) {
;             const unsigned ulane = launder_(ul0);
;             { const int tn = t8 < 3 ? t8 + 1 : 3; RW_LD8(nxt, tn); }
.LBB0_797:
	s_cmpk_lg_i32 s8, 0x60
	s_cselect_b32 s55, s23, 24
	s_mul_i32 s60, s55, 0x1400
	s_mul_hi_u32 s61, s55, 0x1400
	s_add_u32 s60, s4, s60
	v_mov_b32_e32 v149, v0
	v_mov_b32_e32 v42, v2
	v_mov_b32_e32 v0, v2
	s_addc_u32 s61, s5, s61
	s_mul_i32 s62, s55, 0xc00
	v_mov_b32_e32 v17, v1
	v_add_u32_e32 v16, 0x200, v0
	s_mul_hi_u32 s63, s55, 0xc00
	s_add_u32 s62, s6, s62
	v_add_u32_e32 v18, 0x400, v0
	v_mov_b32_e32 v19, v1
	s_addc_u32 s63, s7, s63
	v_lshlrev_b64 v[14:15], 1, v[0:1]
	v_lshlrev_b64 v[16:17], 1, v[16:17]
	v_lshlrev_b64 v[18:19], 1, v[18:19]
	v_lshl_add_u64 v[54:55], s[62:63], 0, v[14:15]
	v_lshl_add_u64 v[56:57], s[62:63], 0, v[16:17]
	s_or_b32 s62, s55, 1
	v_mov_b32_e32 v146, v31
	v_mov_b32_e32 v147, v30
	v_lshl_add_u64 v[30:31], s[60:61], 0, v[14:15]
	v_lshl_add_u64 v[46:47], s[60:61], 0, v[16:17]
	v_lshl_add_u64 v[52:53], s[60:61], 0, v[18:19]
	s_mul_i32 s60, s62, 0x1400
	s_mul_hi_u32 s61, s62, 0x1400
	s_add_u32 s60, s4, s60
	s_addc_u32 s61, s5, s61
	s_mul_hi_u32 s63, s62, 0xc00
	s_mulk_i32 s62, 0xc00
	s_add_u32 s62, s6, s62
	s_addc_u32 s63, s7, s63
	v_mov_b32_e32 v148, v29
	v_lshl_add_u64 v[58:59], s[60:61], 0, v[14:15]
	v_lshl_add_u64 v[96:97], s[60:61], 0, v[16:17]
	v_lshl_add_u64 v[98:99], s[60:61], 0, v[18:19]
	global_load_ushort v0, v[30:31], off nt
	global_load_ushort v29, v[46:47], off nt
	global_load_ushort v45, v[52:53], off nt
	s_nop 0
	global_load_ushort v30, v[54:55], off nt
	global_load_ushort v31, v[56:57], off nt
	global_load_ushort v46, v[58:59], off nt
	global_load_ushort v47, v[96:97], off nt
	global_load_ushort v49, v[98:99], off nt
	v_lshl_add_u64 v[52:53], s[62:63], 0, v[14:15]
	v_lshl_add_u64 v[54:55], s[62:63], 0, v[16:17]
	s_or_b32 s62, s55, 2
	s_mul_i32 s60, s62, 0x1400
	s_mul_hi_u32 s61, s62, 0x1400
	s_add_u32 s60, s4, s60
	s_addc_u32 s61, s5, s61
	s_mul_hi_u32 s63, s62, 0xc00
	s_mulk_i32 s62, 0xc00
	s_add_u32 s62, s6, s62
	s_addc_u32 s63, s7, s63
	v_lshl_add_u64 v[98:99], s[62:63], 0, v[14:15]
	v_lshl_add_u64 v[100:101], s[62:63], 0, v[16:17]
	s_or_b32 s62, s55, 3
	v_lshl_add_u64 v[56:57], s[60:61], 0, v[14:15]
	v_lshl_add_u64 v[58:59], s[60:61], 0, v[16:17]
	v_lshl_add_u64 v[96:97], s[60:61], 0, v[18:19]
	s_mul_i32 s60, s62, 0x1400
	s_mul_hi_u32 s61, s62, 0x1400
	s_add_u32 s60, s4, s60
	s_addc_u32 s61, s5, s61
	s_mul_hi_u32 s63, s62, 0xc00
	s_mulk_i32 s62, 0xc00
	s_add_u32 s62, s6, s62
	s_addc_u32 s63, s7, s63
	v_lshl_add_u64 v[110:111], s[60:61], 0, v[14:15]
	global_load_ushort v52, v[52:53], off nt
	s_nop 0
	global_load_ushort v53, v[54:55], off nt
	s_nop 0
	global_load_ushort v54, v[56:57], off nt
	global_load_ushort v55, v[58:59], off nt
	s_nop 0
	global_load_ushort v56, v[96:97], off nt
	global_load_ushort v57, v[98:99], off nt
	global_load_ushort v58, v[100:101], off nt
	global_load_ushort v59, v[110:111], off nt
	v_lshl_add_u64 v[100:101], s[62:63], 0, v[14:15]
	v_lshl_add_u64 v[110:111], s[62:63], 0, v[16:17]
	s_or_b32 s62, s55, 4
	v_lshl_add_u64 v[96:97], s[60:61], 0, v[16:17]
	v_lshl_add_u64 v[98:99], s[60:61], 0, v[18:19]
	s_mul_i32 s60, s62, 0x1400
	s_mul_hi_u32 s61, s62, 0x1400
	s_add_u32 s60, s4, s60
	s_addc_u32 s61, s5, s61
	s_mul_hi_u32 s63, s62, 0xc00
	s_mulk_i32 s62, 0xc00
	s_add_u32 s62, s6, s62
	s_addc_u32 s63, s7, s63
	v_lshl_add_u64 v[112:113], s[60:61], 0, v[14:15]
	v_lshl_add_u64 v[114:115], s[60:61], 0, v[16:17]
	v_lshl_add_u64 v[116:117], s[60:61], 0, v[18:19]
	v_lshl_add_u64 v[124:125], s[62:63], 0, v[14:15]
	global_load_ushort v96, v[96:97], off nt
	s_nop 0
	global_load_ushort v97, v[98:99], off nt
	s_nop 0
	global_load_ushort v98, v[100:101], off nt
	global_load_ushort v99, v[110:111], off nt
	s_nop 0
	global_load_ushort v100, v[112:113], off nt
	global_load_ushort v101, v[114:115], off nt
	global_load_ushort v102, v[116:117], off nt
	global_load_ushort v106, v[124:125], off nt
	v_lshl_add_u64 v[110:111], s[62:63], 0, v[16:17]
	s_or_b32 s62, s55, 5
	s_mul_i32 s60, s62, 0x1400
	s_mul_hi_u32 s61, s62, 0x1400
	s_add_u32 s60, s4, s60
	s_addc_u32 s61, s5, s61
	s_mul_hi_u32 s63, s62, 0xc00
	s_mulk_i32 s62, 0xc00
	s_add_u32 s62, s6, s62
	s_addc_u32 s63, s7, s63
	v_lshl_add_u64 v[124:125], s[62:63], 0, v[14:15]
	v_lshl_add_u64 v[134:135], s[62:63], 0, v[16:17]
	s_or_b32 s62, s55, 6
	v_lshl_add_u64 v[112:113], s[60:61], 0, v[14:15]
	v_lshl_add_u64 v[114:115], s[60:61], 0, v[16:17]
	v_lshl_add_u64 v[116:117], s[60:61], 0, v[18:19]
	s_mul_i32 s60, s62, 0x1400
	s_mul_hi_u32 s61, s62, 0x1400
	s_add_u32 s60, s4, s60
	s_addc_u32 s61, s5, s61
	s_mul_hi_u32 s63, s62, 0xc00
	s_mulk_i32 s62, 0xc00
	s_add_u32 s62, s6, s62
	s_addc_u32 s63, s7, s63
	s_or_b32 s55, s55, 7
	v_lshl_add_u64 v[136:137], s[60:61], 0, v[14:15]
	v_lshl_add_u64 v[138:139], s[60:61], 0, v[16:17]
	global_load_ushort v110, v[110:111], off nt
	s_nop 0
	global_load_ushort v111, v[112:113], off nt
	s_nop 0
	global_load_ushort v112, v[114:115], off nt
	global_load_ushort v113, v[116:117], off nt
	s_nop 0
	global_load_ushort v114, v[124:125], off nt
	global_load_ushort v115, v[134:135], off nt
	global_load_ushort v116, v[136:137], off nt
	global_load_ushort v117, v[138:139], off nt
	v_lshl_add_u64 v[124:125], s[60:61], 0, v[18:19]
	s_mul_i32 s60, s55, 0x1400
	s_mul_hi_u32 s61, s55, 0x1400
	s_add_u32 s60, s4, s60
	v_lshl_add_u64 v[134:135], s[62:63], 0, v[14:15]
	v_lshl_add_u64 v[136:137], s[62:63], 0, v[16:17]
	s_addc_u32 s61, s5, s61
	s_mul_hi_u32 s63, s55, 0xc00
	s_mulk_i32 s55, 0xc00
	s_add_u32 s62, s6, s55
	s_addc_u32 s63, s7, s63
	v_lshl_add_u64 v[18:19], s[60:61], 0, v[18:19]
	v_lshl_add_u64 v[138:139], s[60:61], 0, v[14:15]
	v_lshl_add_u64 v[140:141], s[60:61], 0, v[16:17]
	v_lshl_add_u64 v[142:143], s[62:63], 0, v[14:15]
	v_lshl_add_u64 v[144:145], s[62:63], 0, v[16:17]
	global_load_ushort v14, v[124:125], off nt
	global_load_ushort v15, v[134:135], off nt
	global_load_ushort v16, v[136:137], off nt
	s_nop 0
	global_load_ushort v124, v[138:139], off nt
	global_load_ushort v125, v[140:141], off nt
	global_load_ushort v17, v[18:19], off nt
	s_nop 0
	global_load_ushort v18, v[142:143], off nt
	global_load_ushort v19, v[144:145], off nt
	v_lshlrev_b32_e32 v134, 16, v147
	s_waitcnt lgkmcnt(0)
; #define LAS __attribute__((address_space(3)))
; __device__ __forceinline__ float bf2f(bf16_t v) { return __uint_as_float(((unsigned)v) << 16); }
; __device__ __forceinline__ bf16_t f2bf(float f) { return (bf16_t)(pk2(f, 0.f) & 0xffffu); }
; __device__ __forceinline__ float sigmoidf_(float x) { return __builtin_amdgcn_rcpf(1.f + __expf(-x)); }
; __device__ __forceinline__ float wave_sum_fast(float x) { x = reduce16(x); return (rl_(x, 0) + rl_(x, 16)) + (rl_(x, 32) + rl_(x, 48)); }
; __device__ __forceinline__ void rwkv_phaseA(const Ctx& F, LAS unsigned char* W, unsigned char* X, int b, int h, int c) {
;     ...
;             for (int tt = 0; tt < 8; ++tt) {
;                 const int t = 8 * t8 + tt;
;                 const float r0 = bf2f(cur[tt][0]), k0 = bf2f(cur[tt][1]), v0 = bf2f(cur[tt][2]);
;                 const float r = r0 + (pr_ - r0) * mu_r, k = k0 + (pk_ - k0) * mu_k, v = v0 + (pv_ - v0) * mu_v; pr_ = r0; pk_ = k0; pv_ = v0;
;                 Bc += -0.6065306597126334f * sigmoidf_(w0 + bf2f(cur[tt][3]));
;                 const float ct = __expf(Bc), ci = __expf(-Bc);
;                 const float a = sigmoidf_(a0 + bf2f(cur[tt][4]));
;                 float kk = k * k_k; const float km = k * (1.0f + (a - 1.0f) * k_a);
;                 const float s_n = wave_sum_fast(kk * kk), s_b = wave_sum_fast(r * km * r_k);
;                 kk = kk * __builtin_amdgcn_rsqf(fmaxf(s_n, 1e-24f));
;                 const float Ak = kk * a * ci, Kc = km * ci, Dk = kk * cprev, Rk = r * ct; cprev = ct;
;                 const bf16_t ab = f2bf(Ak), db = f2bf(Dk), vb = f2bf(v);
;                 *(LAS bf16_t*)(W + RA_ZLO + t * 144 + 2 * lane) = ab; *(LAS bf16_t*)(W + RA_ZHI + t * 144 + 2 * lane) = f2bf(Kc);
;                 *(LAS bf16_t*)(W + RA_ELO + t * 144 + 2 * lane) = db; *(LAS bf16_t*)(W + RA_EHI + t * 144 + 2 * lane) = f2bf(Rk);
;                 if (tt & 1) { at8[tt >> 1] |= (unsigned)ab << 16; dt8[tt >> 1] |= (unsigned)db << 16; vt8[tt >> 1] |= (unsigned)vb << 16; } else { at8[tt >> 1] = ab; dt8[tt >> 1] = db; vt8[tt >> 1] = vb; }
;                 if (lane == 0) *(float*)(X + RX_BON + 4 * t) = s_b;
	v_add_f32_e32 v134, v23, v134
	v_mul_f32_e32 v134, 0xbfb8aa3b, v134
	v_exp_f32_e32 v134, v134
	v_lshlrev_b32_e32 v137, 16, v149
	v_lshlrev_b32_e32 v136, 16, v148
	v_sub_f32_e32 v12, v12, v137
	v_fma_f32 v135, v20, v12, v137
	v_sub_f32_e32 v12, v13, v136
	v_fma_f32 v13, v21, v12, v136
	v_add_f32_e32 v12, 1.0, v134
	v_lshlrev_b32_e32 v134, 16, v146
	v_add_f32_e32 v134, v24, v134
	v_mul_f32_e32 v134, 0xbfb8aa3b, v134
	v_exp_f32_e32 v134, v134
	v_mul_f32_e32 v139, v25, v13
	v_rcp_f32_e32 v12, v12
	v_add_f32_e32 v134, 1.0, v134
	v_rcp_f32_e32 v134, v134
	v_fmac_f32_e32 v38, 0xbf1b4598, v12
	v_mul_f32_e32 v138, 0xbfb8aa3b, v38
	v_mul_f32_e32 v12, 0x3fb8aa3b, v38
	v_add_f32_e32 v140, -1.0, v134
	v_fma_f32 v140, v26, v140, 1.0
	v_mul_f32_e32 v13, v140, v13
	v_mul_f32_e32 v140, v139, v139
	v_exp_f32_e32 v138, v138
	v_exp_f32_e32 v12, v12
	v_mov_b32_dpp v140, v140 quad_perm:[1,0,3,2] row_mask:0xf bank_mask:0xf bound_ctrl:1
	v_fmac_f32_e32 v140, v139, v139
	s_nop 1
	v_add_f32_dpp v140, v140, v140 quad_perm:[2,3,0,1] row_mask:0xf bank_mask:0xf bound_ctrl:1
	s_nop 1
	v_add_f32_dpp v140, v140, v140 row_half_mirror row_mask:0xf bank_mask:0xf bound_ctrl:1
	s_nop 1
	v_add_f32_dpp v140, v140, v140 row_mirror row_mask:0xf bank_mask:0xf bound_ctrl:1
	s_nop 0
	v_readlane_b32 s60, v140, 16
	v_readlane_b32 s55, v140, 0
	s_nop 0
	v_mov_b32_e32 v141, s60
	v_readlane_b32 s60, v140, 48
	v_add_f32_e32 v141, s55, v141
	v_readlane_b32 s55, v140, 32
	v_mov_b32_e32 v140, s60
	s_nop 0
	v_add_f32_e32 v140, s55, v140
	v_add_f32_e32 v140, v141, v140
	v_max_f32_e32 v140, 0x179abe15, v140
	v_rsq_f32_e32 v140, v140
	v_mul_f32_e32 v141, v135, v13
	v_mul_f32_e32 v142, v27, v141
	v_mul_f32_e32 v13, v138, v13
	v_mul_f32_e32 v139, v139, v140
	v_mov_b32_dpp v142, v142 quad_perm:[1,0,3,2] row_mask:0xf bank_mask:0xf bound_ctrl:1
	v_fmac_f32_e32 v142, v27, v141
	v_mul_f32_e32 v134, v134, v139
	v_mul_f32_e32 v134, v138, v134
	v_add_f32_dpp v141, v142, v142 quad_perm:[2,3,0,1] row_mask:0xf bank_mask:0xf bound_ctrl:1
	v_mul_f32_e32 v133, v133, v139
	v_mul_f32_e32 v138, v12, v135
	v_add_f32_dpp v141, v141, v141 row_half_mirror row_mask:0xf bank_mask:0xf bound_ctrl:1
	v_cvt_pk_bf16_f32 v135, v134, s0
	v_cvt_pk_bf16_f32 v13, v13, s0
	v_add_f32_dpp v141, v141, v141 row_mirror row_mask:0xf bank_mask:0xf bound_ctrl:1
	v_cvt_pk_bf16_f32 v134, v133, s0
	v_readlane_b32 s60, v141, 0
	v_readlane_b32 s55, v141, 16
	v_readlane_b32 s61, v141, 32
	v_readlane_b32 s64, v141, 48
	ds_write_b16 v36, v135
	ds_write_b16 v36, v13 offset:9728
	ds_write_b16 v36, v134 offset:14336
	v_cvt_pk_bf16_f32 v13, v138, s0
	ds_write_b16 v36, v13 offset:18944
	s_and_saveexec_b64 s[62:63], vcc
	s_cbranch_execz .LBB0_799
	v_mov_b32_e32 v138, s55
	v_mov_b32_e32 v139, s64
	v_pk_add_f32 v[138:139], s[60:61], v[138:139]
	s_add_u32 s60, s91, s8
	v_add_f32_e32 v13, v138, v139
	s_addc_u32 s61, s92, s9
	global_store_dword v68, v13, s[60:61] offset:2304

; __device__ __forceinline__ unsigned launder_(unsigned x) { asm volatile("" : "+v"(x)); return x; }
; __device__ __forceinline__ void rwkv_chunked_bh(const Ctx& F, int b, int h) {
;     ...
;             const unsigned o128 = launder_((unsigned)(i * 128 + 16 * g)), o64 = launder_((unsigned)(i * 64 + 16 * g)), ulane = launder_((unsigned)lane);
; #pragma unroll
;             for (int q = 0; q < 2; ++q) { const int kt = 2 * kh + q;
;                 ng[q][0] = glb16(X + RX_NGT + 16 * kt * 128 + o128); ng[q][1] = glb16(X + RX_NGT + 16 * kt * 128 + 64 + o128);
;                 hf[q] = glb16(X + RX_HT + 16 * kt * 64 + o64); c4[q] = *(const f32x4*)(X + RX_CC + 16 * kt * 4 + (unsigned)(16 * g)); }
;             qf[0] = glb16(X + RX_QT + 16 * kh * 128 + o128); qf[1] = glb16(X + RX_QT + 16 * kh * 128 + 64 + o128);
;             wyf = glb16(X + RX_WYT + 16 * kh * 64 + o64); vf = glb16(X + RX_VT + 16 * vt * 64 + o64);
;             RwkvPostIn cur;
; #pragma unroll
;             for (int j = 0; j < 4; ++j) { const int t = c * 32 + w + 8 * j; const size_t row = (size_t)b * S + t; const bf16_t* p = proj + row * IN_EVEN_P + RW_OFF + 1024 + h * 64; const unsigned ul = ulane;
;                 cur.pv0[j] = p[ul]; cur.pv1[j] = t > 0 ? (p - IN_EVEN_P)[ul] : (bf16_t)0; cur.gq[j] = (LO + row * 1536 + 1024 + h * 64)[ul]; cur.bon[j] = *(const float*)(X + RX_BON + 4 * (w + 8 * j)); }
.LBB0_834:
	v_mov_b32_e32 v108, v61
	s_waitcnt vmcnt(2)
	v_mov_b32_e32 v107, v64
	s_waitcnt vmcnt(1)
	v_mov_b32_e32 v106, v65
	s_waitcnt vmcnt(0)
	v_mov_b32_e32 v105, v66
	s_add_u32 s4, s46, s60
	v_mov_b32_e32 v0, v75
	s_addc_u32 s5, s47, s61
	v_mov_b32_e32 v56, v76
	v_lshl_add_u64 v[20:21], s[4:5], 0, v[0:1]
	v_add_co_u32_e32 v16, vcc, s0, v20
	s_add_u32 s4, s46, s62
	v_mov_b32_e32 v57, v1
	v_addc_co_u32_e32 v17, vcc, 0, v21, vcc
	s_addc_u32 s5, s47, s63
	s_mov_b32 vcc_lo, 0x30203000
	v_lshl_add_u64 v[22:23], s[4:5], 0, v[56:57]
	v_add_co_u32_e32 v28, vcc, vcc_lo, v22
	v_lshl_add_u64 v[44:45], s[4:5], 0, v[0:1]
	s_nop 0
	v_addc_co_u32_e32 v29, vcc, 0, v23, vcc
	v_lshl_add_u64 v[22:23], s[46:47], 0, v[2:3]
	s_mov_b32 vcc_lo, 0x30205000
	v_add_co_u32_e32 v36, vcc, vcc_lo, v22
	s_add_u32 s4, s46, s10
	s_nop 0
	v_addc_co_u32_e32 v37, vcc, 0, v23, vcc
	s_mov_b32 vcc_lo, 0x30202000
	s_nop 0
	v_add_co_u32_e32 v24, vcc, vcc_lo, v20
	s_addc_u32 s5, s47, s11
	s_nop 0
	v_addc_co_u32_e32 v25, vcc, 0, v21, vcc
	v_add_co_u32_e32 v44, vcc, s1, v44
	v_mov_b32_e32 v58, v71
	s_nop 0
	v_addc_co_u32_e32 v45, vcc, 0, v45, vcc
	s_add_u32 vcc_lo, s46, s8
	s_addc_u32 vcc_hi, s47, s9
	global_load_dwordx4 v[12:15], v[16:17], off offset:2048
	s_nop 0
	global_load_dwordx4 v[16:19], v[16:17], off offset:2112
	s_nop 0
	global_load_dwordx4 v[20:23], v[24:25], off
	s_nop 0
	global_load_dwordx4 v[24:27], v[24:25], off offset:64
	s_nop 0
	global_load_dwordx4 v[32:35], v[28:29], off offset:2048
	s_nop 0
	global_load_dwordx4 v[28:31], v[28:29], off offset:3072
	s_nop 0
	global_load_dwordx4 v[40:43], v[36:37], off offset:2048
	s_nop 0
	global_load_dwordx4 v[36:39], v[36:37], off offset:2112
	s_nop 0
	global_load_dwordx4 v[52:55], v[44:45], off
	global_load_dwordx4 v[48:51], v[44:45], off offset:64
	v_mov_b32_e32 v59, v1
	global_load_dwordx4 v[44:47], v56, vcc
	s_add_u32 vcc_lo, s46, s64
	v_lshlrev_b64 v[66:67], 1, v[58:59]
	s_addc_u32 vcc_hi, s47, s65
	v_lshl_add_u64 v[64:65], vcc, 0, v[66:67]
	v_add_co_u32_e32 v94, vcc, 0xc200000, v64
	s_cmp_eq_u32 s55, 0
	s_nop 0
	v_addc_co_u32_e32 v95, vcc, 0, v65, vcc
	global_load_dwordx4 v[56:59], v56, s[4:5]
	s_nop 0
	global_load_ushort v94, v[94:95], off offset:3392 nt
	s_cbranch_scc1 .LBB0_837
	v_add_co_u32_e32 v96, vcc, 0xc1ff000, v64
	s_nop 1
	v_addc_co_u32_e32 v97, vcc, 0, v65, vcc
	global_load_ushort v95, v[96:97], off offset:2368 nt
	s_branch .LBB0_838

; #define LAS __attribute__((address_space(3)))
; __device__ __forceinline__ unsigned pk2(float lo, float hi) { f32x2 v = {lo, hi}; bf16x2_t b = __builtin_convertvector(v, bf16x2_t); return __builtin_bit_cast(unsigned, b); }
; #define MFMA16(a, b, c) __builtin_amdgcn_mfma_f32_16x16x32_bf16((a), (b), (c), 0, 0, 0)
; __device__ __forceinline__ void rwkv_chunked_bh(const Ctx& F, int b, int h) {
;     ...
;             for (int j = 0; j < 4; ++j) { const int t = c * 32 + w + 8 * j; const size_t row = (size_t)b * S + t; const bf16_t* p = proj + row * IN_EVEN_P + RW_OFF + 1024 + h * 64; const unsigned ul = ulane;
;                 cur.pv0[j] = p[ul]; cur.pv1[j] = t > 0 ? (p - IN_EVEN_P)[ul] : (bf16_t)0; cur.gq[j] = (LO + row * 1536 + 1024 + h * 64)[ul]; cur.bon[j] = *(const float*)(X + RX_BON + 4 * (w + 8 * j)); }
; #pragma unroll
;             for (int q = 0; q < 2; ++q) *(LAS u32x2*)(Ls + RB_SB + (16 * vt + i) * 144 + (16 * (2 * kh + q) + 4 * g) * 2) = (u32x2){pk2(sT[q][0], sT[q][1]), pk2(sT[q][2], sT[q][3])};
;             __syncthreads();
;             const bf16x8 bs0 = lds16(Ls + RB_SB + (16 * vt + i) * 144 + (8 * g) * 2), bs1 = lds16(Ls + RB_SB + (16 * vt + i) * 144 + (32 + 8 * g) * 2);
;             f32x4 y = MFMA16(qf[0], bs0, ((f32x4){0.f, 0.f, 0.f, 0.f})); y = MFMA16(qf[1], bs1, y); y = MFMA16(wyf, vf, y);
; #pragma unroll
;             for (int q = 0; q < 2; ++q) { f32x4 a = sT[q] * c4[q]; a = MFMA16(ng[q][0], bs0, a); a = MFMA16(ng[q][1], bs1, a); sT[q] = MFMA16(hf[q], vf, a); }
; #pragma unroll
;             for (int r = 0; r < 4; ++r) *(LAS float*)(Ls + RB_YL + ((16 * kh + 4 * g + r) * 64 + 16 * vt + i) * 4) = y[r];
;             if (cc > 0) rwkv_post_chunk(Y, L + ((cc - 1) & 1) * RBSTG + RB_YL, prv, b, h, c - 1, w, lane, mu_v, ln_w, ln_b);
.LBB0_838:
	s_bitcmp1_b32 s23, 0
	s_cselect_b32 s52, 0x4400, 0
	s_add_u32 s4, s46, s66
	s_addc_u32 s5, s47, s67
	v_lshl_add_u64 v[66:67], s[4:5], 0, v[66:67]
	v_add_co_u32_e32 v102, vcc, 0x32200000, v66
	s_add_u32 s4, s46, s6
	s_nop 0
	v_addc_co_u32_e32 v103, vcc, 0, v67, vcc
	v_add_co_u32_e32 v110, vcc, 0xc20a000, v64
	s_addc_u32 s5, s47, s7
	s_nop 0
	v_addc_co_u32_e32 v111, vcc, 0, v65, vcc
	v_add_co_u32_e32 v112, vcc, 0xc209000, v64
	s_nop 1
	v_addc_co_u32_e32 v113, vcc, 0, v65, vcc
	v_add_co_u32_e32 v114, vcc, 0x32206000, v66
	s_nop 1
	v_addc_co_u32_e32 v115, vcc, 0, v67, vcc
	v_add_co_u32_e32 v96, vcc, 0xc214000, v64
	s_nop 1
	v_addc_co_u32_e32 v97, vcc, 0, v65, vcc
	v_add_co_u32_e32 v100, vcc, 0xc213000, v64
	s_nop 1
	v_addc_co_u32_e32 v101, vcc, 0, v65, vcc
	v_add_co_u32_e32 v116, vcc, 0x3220c000, v66
	s_nop 1
	v_addc_co_u32_e32 v117, vcc, 0, v67, vcc
	v_add_co_u32_e32 v118, vcc, 0xc21e000, v64
	s_nop 1
	v_addc_co_u32_e32 v119, vcc, 0, v65, vcc
	v_add_co_u32_e32 v64, vcc, 0xc21d000, v64
	s_nop 1
	v_addc_co_u32_e32 v65, vcc, 0, v65, vcc
	v_add_co_u32_e32 v120, vcc, 0x32212000, v66
	s_nop 1
	v_addc_co_u32_e32 v121, vcc, 0, v67, vcc
	global_load_ushort v99, v[96:97], off offset:3392 nt
	s_nop 0
	global_load_ushort v96, v[100:101], off offset:2368 nt
	global_load_ushort v67, v[116:117], off offset:2048 nt
	s_nop 0
	global_load_ushort v100, v[118:119], off offset:3392 nt
	global_load_ushort v97, v[64:65], off offset:2368 nt
	global_load_ushort v98, v[120:121], off offset:2048 nt
	global_load_ushort v101, v[102:103], off offset:2048 nt
	global_load_dword v61, v68, s[4:5] offset:2304
	global_load_ushort v104, v[110:111], off offset:3392 nt
	s_nop 0
	global_load_ushort v103, v[112:113], off offset:2368 nt
	global_load_ushort v102, v[114:115], off offset:2048 nt
	global_load_dword v64, v68, s[4:5] offset:2336
	global_load_dword v65, v68, s[4:5] offset:2368
	global_load_dword v66, v68, s[4:5] offset:2400
	s_add_i32 s4, s52, 0
	v_add_u32_e32 v0, s4, v77
	v_add3_u32 v109, v0, v78, s80
	v_cvt_pk_bf16_f32 v110, v4, v5
	v_cvt_pk_bf16_f32 v111, v6, v7
	v_cvt_pk_bf16_f32 v112, v8, v9
	v_cvt_pk_bf16_f32 v113, v10, v11
	v_add_u32_e32 v0, v0, v60
	ds_write2_b64 v109, v[110:111], v[112:113] offset1:4
	s_waitcnt lgkmcnt(0)
	s_barrier
	ds_read_b128 v[110:113], v0
	ds_read_b128 v[114:117], v0 offset:64
	s_waitcnt vmcnt(20)
	v_pk_mul_f32 v[6:7], v[6:7], v[42:43]
	v_pk_mul_f32 v[4:5], v[4:5], v[40:41]
	s_waitcnt vmcnt(19)
	v_pk_mul_f32 v[10:11], v[10:11], v[38:39]
	v_pk_mul_f32 v[8:9], v[8:9], v[36:37]
	s_waitcnt vmcnt(18) lgkmcnt(1)
	v_mfma_f32_16x16x32_bf16 v[52:55], v[52:55], v[110:113], 0
	s_add_i32 s4, s4, s88
	v_add3_u32 v0, s4, v79, v81
	s_cmp_eq_u32 s23, 0
	v_mfma_f32_16x16x32_bf16 v[4:7], v[12:15], v[110:113], v[4:7]
	v_mfma_f32_16x16x32_bf16 v[8:11], v[20:23], v[110:113], v[8:11]
	s_waitcnt vmcnt(17) lgkmcnt(0)
	v_mfma_f32_16x16x32_bf16 v[48:51], v[48:51], v[114:117], v[52:55]
	v_mfma_f32_16x16x32_bf16 v[4:7], v[16:19], v[114:117], v[4:7]
	v_mfma_f32_16x16x32_bf16 v[8:11], v[24:27], v[114:117], v[8:11]
	s_waitcnt vmcnt(16)
	v_mfma_f32_16x16x32_bf16 v[4:7], v[32:35], v[44:47], v[4:7]
	v_mfma_f32_16x16x32_bf16 v[8:11], v[28:31], v[44:47], v[8:11]
	s_waitcnt vmcnt(15)
	v_mfma_f32_16x16x32_bf16 v[12:15], v[56:59], v[44:47], v[48:51]
	s_nop 7
	ds_write2st64_b32 v0, v12, v13 offset0:36 offset1:37
	ds_write2st64_b32 v0, v14, v15 offset0:38 offset1:39
	s_cbranch_scc1 .LBB0_840
	s_andn2_b32 s4, 1, s23
	s_mulk_i32 s4, 0x4400
	v_add_u32_e32 v13, s4, v80
	v_mov_b32_e32 v0, v71
	v_add_u32_e32 v12, s81, v13
	ds_read_b32 v12, v12 offset:9216
	v_add_u32_e32 v14, s83, v13
	v_add_u32_e32 v15, s85, v13
	v_add_u32_e32 v13, s87, v13
	ds_read_b32 v18, v14 offset:9216
	ds_read_b32 v15, v15 offset:9216
	ds_read_b32 v14, v13 offset:9216
	s_waitcnt lgkmcnt(3)
	v_add_f32_dpp v13, v12, v12 quad_perm:[1,0,3,2] row_mask:0xf bank_mask:0xf bound_ctrl:1
	s_nop 1
	v_add_f32_dpp v13, v13, v13 quad_perm:[2,3,0,1] row_mask:0xf bank_mask:0xf bound_ctrl:1
	s_nop 1
	v_add_f32_dpp v13, v13, v13 row_half_mirror row_mask:0xf bank_mask:0xf bound_ctrl:1
	s_nop 1
	v_add_f32_dpp v13, v13, v13 row_mirror row_mask:0xf bank_mask:0xf bound_ctrl:1
	s_nop 0
	v_readlane_b32 s5, v13, 16
	v_readlane_b32 s4, v13, 0
	s_nop 0
	v_mov_b32_e32 v16, s5
	v_readlane_b32 s5, v13, 48
	v_add_f32_e32 v16, s4, v16
	v_readlane_b32 s4, v13, 32
	v_mov_b32_e32 v13, s5
	s_nop 0
	v_add_f32_e32 v13, s4, v13
	v_add_f32_e32 v13, v16, v13
	v_mul_f32_e32 v16, v12, v12
	s_nop 1
	v_mov_b32_dpp v16, v16 quad_perm:[1,0,3,2] row_mask:0xf bank_mask:0xf bound_ctrl:1
	v_fmac_f32_e32 v16, v12, v12
	v_fmac_f32_e32 v12, 0xbc800000, v13
	s_nop 0
	v_add_f32_dpp v16, v16, v16 quad_perm:[2,3,0,1] row_mask:0xf bank_mask:0xf bound_ctrl:1
	s_nop 1
	v_add_f32_dpp v16, v16, v16 row_half_mirror row_mask:0xf bank_mask:0xf bound_ctrl:1
	s_nop 1
	v_add_f32_dpp v16, v16, v16 row_mirror row_mask:0xf bank_mask:0xf bound_ctrl:1
	s_nop 0
	v_readlane_b32 s5, v16, 16
	v_readlane_b32 s4, v16, 0
	s_nop 0
	v_mov_b32_e32 v17, s5
	v_readlane_b32 s5, v16, 48
	v_add_f32_e32 v17, s4, v17
	v_readlane_b32 s4, v16, 32
	v_mov_b32_e32 v16, s5
	s_nop 0
	v_add_f32_e32 v16, s4, v16
	v_add_f32_e32 v16, v17, v16
	v_mul_f32_e32 v17, 0x3c800000, v13
	v_mul_f32_e32 v17, v17, v17
	v_fma_f32 v16, v16, s90, -v17
	v_max_f32_e32 v16, 0, v16
	v_add_f32_e32 v16, 0x3a27c5ac, v16
	v_rsq_f32_e32 v250, v16
	s_add_u32 s4, s46, s68
	v_mov_b32_e32 v13, v250
	v_mul_f32_e32 v12, v12, v13
	v_lshlrev_b32_e32 v13, 16, v91
	v_lshlrev_b32_e32 v16, 16, v92
	v_sub_f32_e32 v16, v16, v13
	v_fma_f32 v12, v73, v12, v74
	v_fmac_f32_e32 v13, v72, v16
	v_fmac_f32_e32 v12, v13, v108
	v_lshlrev_b32_e32 v13, 16, v93
	v_mul_f32_e32 v12, v12, v13
	v_cvt_pk_bf16_f32 v19, v12, s0
	s_waitcnt lgkmcnt(2)
; #define LAS __attribute__((address_space(3)))
; __device__ __forceinline__ float bf2f(bf16_t v) { return __uint_as_float(((unsigned)v) << 16); }
; __device__ __forceinline__ bf16_t f2bf(float f) { return (bf16_t)(pk2(f, 0.f) & 0xffffu); }
; __device__ __forceinline__ float wave_sum_fast(float x) { x = reduce16(x); return (rl_(x, 0) + rl_(x, 16)) + (rl_(x, 32) + rl_(x, 48)); }
; __device__ __forceinline__ unsigned launder_(unsigned x) { asm volatile("" : "+v"(x)); return x; }
; __device__ __forceinline__ void rwkv_post_chunk(bf16_t* Y, const LAS unsigned char* Yp, const RwkvPostIn& in, int b, int h, int c, int w, int lane, float mu_v, float ln_w, float ln_b) {
;     const unsigned ulane = launder_((unsigned)lane);
; #pragma unroll
;     for (int j = 0; j < 4; ++j) {
;         const int tl = w + 8 * j; const size_t row = (size_t)b * S + c * 32 + tl;
;         const float yv = *(const LAS float*)(Yp + (tl * 64 + lane) * 4);
;         const float s1 = wave_sum_fast(yv), s2 = wave_sum_fast(yv * yv);
;         const float mean = s1 * (1.0f / 64.f), var = fmaxf(s2 * (1.0f / 64.f) - mean * mean, 0.f);
;         const float yn = (yv - mean) * (1.0f / sqrtf(var + 64e-5f)) * ln_w + ln_b;
;         float v = bf2f(in.pv0[j]); v += (bf2f(in.pv1[j]) - v) * mu_v;
;         (Y + row * D + 512 + h * 64)[ulane] = f2bf((yn + in.bon[j] * v) * bf2f(in.gq[j]));
;     }
	v_add_f32_dpp v12, v18, v18 quad_perm:[1,0,3,2] row_mask:0xf bank_mask:0xf bound_ctrl:1
	s_nop 1
	v_add_f32_dpp v12, v12, v12 quad_perm:[2,3,0,1] row_mask:0xf bank_mask:0xf bound_ctrl:1
	s_nop 1
	v_add_f32_dpp v12, v12, v12 row_half_mirror row_mask:0xf bank_mask:0xf bound_ctrl:1
	s_nop 1
	v_add_f32_dpp v12, v12, v12 row_mirror row_mask:0xf bank_mask:0xf bound_ctrl:1
	s_nop 0
	v_readlane_b32 s52, v12, 16
	v_readlane_b32 s5, v12, 0
	s_nop 0
	v_mov_b32_e32 v13, s52
	v_readlane_b32 s52, v12, 48
	v_add_f32_e32 v13, s5, v13
	v_readlane_b32 s5, v12, 32
	v_mov_b32_e32 v12, s52
	s_nop 0
	v_add_f32_e32 v12, s5, v12
	v_add_f32_e32 v20, v13, v12
	v_mul_f32_e32 v12, v18, v18
	s_nop 1
	v_mov_b32_dpp v12, v12 quad_perm:[1,0,3,2] row_mask:0xf bank_mask:0xf bound_ctrl:1
	v_fmac_f32_e32 v12, v18, v18
	v_fmac_f32_e32 v18, 0xbc800000, v20
	s_nop 0
	v_add_f32_dpp v12, v12, v12 quad_perm:[2,3,0,1] row_mask:0xf bank_mask:0xf bound_ctrl:1
	s_nop 1
	v_add_f32_dpp v12, v12, v12 row_half_mirror row_mask:0xf bank_mask:0xf bound_ctrl:1
	s_nop 1
	v_add_f32_dpp v12, v12, v12 row_mirror row_mask:0xf bank_mask:0xf bound_ctrl:1
	s_nop 0
	v_readlane_b32 s52, v12, 16
	v_readlane_b32 s5, v12, 0
	s_nop 0
	v_mov_b32_e32 v13, s52
	v_readlane_b32 s52, v12, 48
	v_add_f32_e32 v13, s5, v13
	v_readlane_b32 s5, v12, 32
	v_mov_b32_e32 v12, s52
	s_mov_b32 s52, 0x41f0000
	v_add_f32_e32 v12, s5, v12
	v_add_f32_e32 v12, v13, v12
	v_mul_f32_e32 v13, 0x3c800000, v20
	v_mul_f32_e32 v13, v13, v13
	v_fma_f32 v12, v12, s90, -v13
	v_max_f32_e32 v12, 0, v12
	v_add_f32_e32 v12, 0x3a27c5ac, v12
	v_rsq_f32_e32 v251, v12
	s_addc_u32 s5, s47, s69
	s_nop 0
	v_lshl_add_u64 v[12:13], v[0:1], 1, s[4:5]
	v_add_co_u32_e32 v16, vcc, s52, v12
	s_mov_b32 s52, 0x41f4000
	s_nop 0
	v_addc_co_u32_e32 v17, vcc, 0, v13, vcc
	global_store_short v[16:17], v19, off offset:1024
	v_mov_b32_e32 v0, v251
	v_lshlrev_b32_e32 v16, 16, v88
	v_lshlrev_b32_e32 v17, 16, v89
	v_sub_f32_e32 v17, v17, v16
	v_fmac_f32_e32 v16, v72, v17
	v_mul_f32_e32 v0, v18, v0
	s_waitcnt lgkmcnt(1)
	v_add_f32_dpp v17, v15, v15 quad_perm:[1,0,3,2] row_mask:0xf bank_mask:0xf bound_ctrl:1
	v_fma_f32 v0, v73, v0, v74
	v_fmac_f32_e32 v0, v16, v107
	v_add_f32_dpp v17, v17, v17 quad_perm:[2,3,0,1] row_mask:0xf bank_mask:0xf bound_ctrl:1
	v_lshlrev_b32_e32 v16, 16, v90
	v_mul_f32_e32 v0, v0, v16
	v_add_f32_dpp v17, v17, v17 row_half_mirror row_mask:0xf bank_mask:0xf bound_ctrl:1
	v_cvt_pk_bf16_f32 v0, v0, s0
	s_nop 0
	v_add_f32_dpp v17, v17, v17 row_mirror row_mask:0xf bank_mask:0xf bound_ctrl:1
	s_nop 0
	v_readlane_b32 s5, v17, 16
	v_readlane_b32 s4, v17, 0
	s_nop 0
	v_mov_b32_e32 v18, s5
	v_readlane_b32 s5, v17, 48
	v_add_f32_e32 v18, s4, v18
	v_readlane_b32 s4, v17, 32
	v_mov_b32_e32 v17, s5
	s_nop 0
	v_add_f32_e32 v17, s4, v17
	v_add_f32_e32 v18, v18, v17
	v_mul_f32_e32 v17, v15, v15
	s_nop 1
	v_mov_b32_dpp v17, v17 quad_perm:[1,0,3,2] row_mask:0xf bank_mask:0xf bound_ctrl:1
	v_fmac_f32_e32 v17, v15, v15
	v_fmac_f32_e32 v15, 0xbc800000, v18
	s_nop 0
	v_add_f32_dpp v17, v17, v17 quad_perm:[2,3,0,1] row_mask:0xf bank_mask:0xf bound_ctrl:1
	s_nop 1
	v_add_f32_dpp v17, v17, v17 row_half_mirror row_mask:0xf bank_mask:0xf bound_ctrl:1
	s_nop 1
	v_add_f32_dpp v17, v17, v17 row_mirror row_mask:0xf bank_mask:0xf bound_ctrl:1
	s_nop 0
	v_readlane_b32 s5, v17, 16
	v_readlane_b32 s4, v17, 0
	s_nop 0
	v_mov_b32_e32 v19, s5
	v_readlane_b32 s5, v17, 48
	v_add_f32_e32 v19, s4, v19
	v_readlane_b32 s4, v17, 32
	v_mov_b32_e32 v17, s5
	s_nop 0
	v_add_f32_e32 v17, s4, v17
	v_add_f32_e32 v17, v19, v17
	v_mul_f32_e32 v19, 0x3c800000, v18
	v_mul_f32_e32 v19, v19, v19
	v_fma_f32 v17, v17, s90, -v19
	v_max_f32_e32 v17, 0, v17
	v_add_f32_e32 v17, 0x3a27c5ac, v17
	v_rsq_f32_e32 v252, v17
	v_add_co_u32_e32 v16, vcc, s52, v12
	s_mov_b32 s52, 0x41f8000
	s_nop 0
	v_addc_co_u32_e32 v17, vcc, 0, v13, vcc
	global_store_short v[16:17], v0, off offset:1024
	v_mov_b32_e32 v0, v252
	v_mul_f32_e32 v0, v15, v0
	v_lshlrev_b32_e32 v15, 16, v85
	v_lshlrev_b32_e32 v16, 16, v86
	v_sub_f32_e32 v16, v16, v15
	v_fmac_f32_e32 v15, v72, v16
	v_fma_f32 v0, v73, v0, v74
	s_waitcnt lgkmcnt(0)
	v_add_f32_dpp v16, v14, v14 quad_perm:[1,0,3,2] row_mask:0xf bank_mask:0xf bound_ctrl:1
	v_fmac_f32_e32 v0, v15, v106
	v_lshlrev_b32_e32 v15, 16, v87
	v_add_f32_dpp v16, v16, v16 quad_perm:[2,3,0,1] row_mask:0xf bank_mask:0xf bound_ctrl:1
	v_mul_f32_e32 v0, v0, v15
	v_cvt_pk_bf16_f32 v0, v0, s0
	v_add_f32_dpp v16, v16, v16 row_half_mirror row_mask:0xf bank_mask:0xf bound_ctrl:1
	s_nop 1
	v_add_f32_dpp v16, v16, v16 row_mirror row_mask:0xf bank_mask:0xf bound_ctrl:1
	s_nop 0
	v_readlane_b32 s5, v16, 16
	v_readlane_b32 s4, v16, 0
	s_nop 0
	v_mov_b32_e32 v17, s5
	v_readlane_b32 s5, v16, 48
	v_add_f32_e32 v17, s4, v17
	v_readlane_b32 s4, v16, 32
	v_mov_b32_e32 v16, s5
	s_nop 0
	v_add_f32_e32 v16, s4, v16
	v_add_f32_e32 v18, v17, v16
	v_mul_f32_e32 v16, v14, v14
	s_nop 1
	v_mov_b32_dpp v16, v16 quad_perm:[1,0,3,2] row_mask:0xf bank_mask:0xf bound_ctrl:1
	v_fmac_f32_e32 v16, v14, v14
	v_fmac_f32_e32 v14, 0xbc800000, v18
	s_nop 0
	v_add_f32_dpp v16, v16, v16 quad_perm:[2,3,0,1] row_mask:0xf bank_mask:0xf bound_ctrl:1
	s_nop 1
	v_add_f32_dpp v16, v16, v16 row_half_mirror row_mask:0xf bank_mask:0xf bound_ctrl:1
	s_nop 1
	v_add_f32_dpp v16, v16, v16 row_mirror row_mask:0xf bank_mask:0xf bound_ctrl:1
	s_nop 0
	v_readlane_b32 s5, v16, 16
	v_readlane_b32 s4, v16, 0
	s_nop 0
	v_mov_b32_e32 v17, s5
	v_readlane_b32 s5, v16, 48
	v_add_f32_e32 v17, s4, v17
	v_readlane_b32 s4, v16, 32
	v_mov_b32_e32 v16, s5
	s_nop 0
	v_add_f32_e32 v16, s4, v16
	v_add_f32_e32 v16, v17, v16
	v_mul_f32_e32 v17, 0x3c800000, v18
	v_mul_f32_e32 v17, v17, v17
	v_fma_f32 v16, v16, s90, -v17
	v_max_f32_e32 v16, 0, v16
	v_add_f32_e32 v16, 0x3a27c5ac, v16
	v_rsq_f32_e32 v253, v16
	v_add_co_u32_e32 v16, vcc, s52, v12
	s_nop 1
	v_addc_co_u32_e32 v17, vcc, 0, v13, vcc
	global_store_short v[16:17], v0, off offset:1024
	v_mov_b32_e32 v0, v253
	v_mul_f32_e32 v0, v14, v0
	v_lshlrev_b32_e32 v14, 16, v82
	v_lshlrev_b32_e32 v15, 16, v83
	v_sub_f32_e32 v15, v15, v14
	v_fma_f32 v0, v73, v0, v74
	v_fmac_f32_e32 v14, v72, v15
	v_fmac_f32_e32 v0, v14, v105
	v_lshlrev_b32_e32 v14, 16, v84
	v_mul_f32_e32 v0, v0, v14
	v_add_co_u32_e32 v12, vcc, 0x41fc000, v12
	v_cvt_pk_bf16_f32 v0, v0, s0
	s_nop 0
	v_addc_co_u32_e32 v13, vcc, 0, v13, vcc
	global_store_short v[12:13], v0, off offset:1024
